# scanA/scanC chunk loads prefetched one chunk ahead into shadow registers (on top of dil_attn rewrite)
# speedup vs baseline: 1.0316x; 1.0093x over previous
.LBB0_292:
	v_readlane_b32 s28, v253, 27
.Lsc_reinit:
	v_readlane_b32 s2, v251, 55
	v_readlane_b32 s3, v251, 56
	v_mov_b32_e32 v0, v179
	s_andn2_b64 vcc, exec, s[2:3]
	s_cbranch_vccnz .LBB0_303
	v_and_b32_e32 v2, 15, v0
	v_readlane_b32 s2, v251, 61
	v_lshlrev_b32_e32 v176, 2, v2
	v_readlane_b32 s3, v251, 62
	v_and_b32_e32 v6, 0x7f, v0
	v_and_b32_e32 v1, 63, v0
	v_lshl_add_u64 v[24:25], s[2:3], 0, v[176:177]
	v_readlane_b32 s2, v252, 1
	v_lshlrev_b32_e32 v176, 2, v6
	v_readlane_b32 s3, v252, 2
	v_lshlrev_b32_e32 v8, 1, v1
	v_mov_b32_e32 v9, v177
	v_lshl_add_u64 v[26:27], s[2:3], 0, v[176:177]
	v_readlane_b32 s2, v251, 63
	v_readlane_b32 s3, v252, 0
	v_bfe_u32 v3, v0, 4, 2
	v_ashrrev_i32_e32 v5, 6, v0
	v_ashrrev_i32_e32 v12, 7, v0
	v_lshl_add_u64 v[28:29], s[2:3], 0, v[8:9]
	v_readlane_b32 s2, v253, 44
	s_movk_i32 s14, 0x90
	v_lshlrev_b32_e32 v11, 2, v3
	v_lshlrev_b32_e32 v54, 4, v12
	v_lshl_add_u32 v56, v0, 2, s2
	v_mad_u32_u24 v9, v1, s14, 0
	v_add_u32_e32 v57, s2, v176
	s_movk_i32 s2, 0x80
	v_lshlrev_b32_e32 v1, 5, v5
	v_lshlrev_b32_e32 v3, 3, v3
	v_readlane_b32 s5, v253, 46
	v_and_b32_e32 v15, 48, v0
	v_cmp_gt_u32_e32 vcc, s2, v0
	v_add3_u32 v3, s5, v1, v3
	v_and_b32_e32 v8, 32, v1
	v_or_b32_e32 v1, v54, v2
	v_add_u32_e32 v10, 0, v15
	s_movk_i32 s2, 0x110
	v_lshlrev_b32_e32 v7, 4, v5
	v_readlane_b32 s4, v253, 45
	v_mad_u64_u32 v[30:31], s[2:3], v1, s2, v[10:11]
	v_and_b32_e32 v0, 0xffffffc0, v0
	v_or_b32_e32 v4, v11, v7
	v_or_b32_e32 v31, v11, v54
	v_add_u32_e32 v11, s4, v0
	v_or_b32_e32 v0, v7, v2
	v_mad_u64_u32 v[32:33], s[2:3], v0, s14, v[10:11]
	v_lshlrev_b32_e32 v0, 7, v1
	v_sub_u32_e32 v33, v30, v0
	v_or_b32_e32 v0, 1, v4
	v_ashrrev_i32_e32 v1, 31, v0
	v_lshlrev_b64 v[36:37], 10, v[0:1]
	v_or_b32_e32 v0, 2, v4
	v_ashrrev_i32_e32 v1, 31, v0
	v_lshlrev_b64 v[38:39], 10, v[0:1]
	v_or_b32_e32 v0, 3, v4
	v_ashrrev_i32_e32 v1, 31, v0
	s_movk_i32 s2, 0x880
	v_lshlrev_b64 v[40:41], 10, v[0:1]
	v_mul_lo_u32 v0, v12, s2
	v_or_b32_e32 v63, 2, v54
	v_or_b32_e32 v0, v0, v6
	s_movk_i32 s2, 0x88
	v_lshl_add_u32 v106, v0, 1, 0
	v_mad_u64_u32 v[0:1], s[2:3], v63, s2, v[6:7]
	v_or_b32_e32 v1, v8, v2
	v_add_u32_e32 v58, s4, v176
	v_lshlrev_b32_e32 v14, 5, v12
	v_add_u32_e32 v16, s5, v15
	v_cmp_lt_i32_e64 s[4:5], 0, v12
	v_cmp_lt_i32_e64 s[6:7], 1, v12
	v_cmp_lt_i32_e64 s[8:9], 2, v12
	v_cmp_lt_i32_e64 s[10:11], 3, v12
	v_mul_u32_u24_e32 v12, 0x88, v1
	v_lshlrev_b32_e32 v12, 1, v12
	v_readlane_b32 s2, v251, 59
	v_lshlrev_b32_e32 v55, 3, v5
	v_ashrrev_i32_e32 v5, 31, v4
	v_add_u32_e32 v114, v10, v12
	v_add_u32_e32 v115, v16, v12
	v_or_b32_e32 v12, 16, v1
	v_readlane_b32 s3, v251, 60
	v_mul_u32_u24_e32 v17, 0x88, v12
	v_lshlrev_b32_e32 v17, 1, v17
	v_lshl_add_u64 v[42:43], v[4:5], 2, s[2:3]
	v_readlane_b32 s2, v251, 57
	v_or_b32_e32 v118, 1, v31
	v_or_b32_e32 v119, 2, v31
	v_or_b32_e32 v120, 3, v31
	v_lshlrev_b32_e32 v176, 1, v6
	v_readlane_b32 s3, v251, 58
	v_mad_u32_u24 v13, v6, s14, 0
	v_or_b32_e32 v61, 1, v54
	v_or_b32_e32 v65, 3, v54
	v_or_b32_e32 v67, 4, v54
	v_or_b32_e32 v69, 5, v54
	v_or_b32_e32 v71, 6, v54
	v_or_b32_e32 v73, 7, v54
	v_or_b32_e32 v75, 8, v54
	v_or_b32_e32 v77, 9, v54
	v_or_b32_e32 v79, 10, v54
	v_or_b32_e32 v81, 11, v54
	v_or_b32_e32 v83, 12, v54
	v_or_b32_e32 v85, 13, v54
	v_or_b32_e32 v87, 14, v54
	v_or_b32_e32 v89, 15, v54
	v_or_b32_e32 v92, 1, v55
	v_or_b32_e32 v94, 2, v55
	v_or_b32_e32 v96, 3, v55
	v_or_b32_e32 v98, 4, v55
	v_or_b32_e32 v100, 5, v55
	v_or_b32_e32 v102, 6, v55
	v_or_b32_e32 v104, 7, v55
	v_lshl_add_u32 v107, v0, 1, 0
	v_mul_u32_u24_e32 v0, 0x110, v2
	v_add_u32_e32 v116, v10, v17
	v_add_u32_e32 v117, v16, v17
	v_lshl_add_u32 v16, v1, 1, 0
	v_cmp_gt_i32_e64 s[12:13], v1, v31
	v_mul_lo_u32 v17, v31, s14
	v_cmp_gt_i32_e64 s[14:15], v1, v118
	v_cmp_gt_i32_e64 s[16:17], v1, v119
	v_cmp_gt_i32_e64 s[18:19], v1, v120
	v_cmp_gt_i32_e64 s[20:21], v12, v31
	v_cmp_gt_i32_e64 s[22:23], v12, v118
	v_cmp_gt_i32_e64 s[24:25], v12, v119
	v_cmp_gt_i32_e64 s[38:39], v12, v120
	v_mul_u32_u24_e32 v18, 0x90, v2
	v_mul_u32_u24_e32 v1, 0x90, v1
	v_mul_u32_u24_e32 v12, 0x90, v12
	v_lshl_add_u64 v[44:45], s[2:3], 0, v[176:177]
	v_readlane_b32 s2, v253, 27
	v_lshlrev_b64 v[34:35], 10, v[4:5]
	v_sub_u32_e32 v59, 63, v31
	v_sub_u32_e32 v60, 63, v54
	v_sub_u32_e32 v62, 63, v61
	v_sub_u32_e32 v64, 63, v63
	v_sub_u32_e32 v66, 63, v65
	v_sub_u32_e32 v68, 63, v67
	v_sub_u32_e32 v70, 63, v69
	v_sub_u32_e32 v72, 63, v71
	v_sub_u32_e32 v74, 63, v73
	v_sub_u32_e32 v76, 63, v75
	v_sub_u32_e32 v78, 63, v77
	v_sub_u32_e32 v80, 63, v79
	v_sub_u32_e32 v82, 63, v81
	v_sub_u32_e32 v84, 63, v83
	v_sub_u32_e32 v86, 63, v85
	v_sub_u32_e32 v88, 63, v87
	v_sub_u32_e32 v90, 63, v89
	v_sub_u32_e32 v91, 63, v55
	v_sub_u32_e32 v93, 63, v92
	v_sub_u32_e32 v95, 63, v94
	v_sub_u32_e32 v97, 63, v96
	v_sub_u32_e32 v99, 63, v98
	v_sub_u32_e32 v101, 63, v100
	v_sub_u32_e32 v103, 63, v102
	v_sub_u32_e32 v105, 63, v104
	v_add_u32_e32 v108, 0x220, v107
	v_add_u32_e32 v109, 0x440, v107
	v_add_u32_e32 v110, 0x660, v107
	v_add_u32_e32 v111, 0x880, v107
	v_add_u32_e32 v112, 0xaa0, v107
	v_add_u32_e32 v113, 0xcc0, v107
	v_sub_u32_e32 v121, 63, v118
	v_sub_u32_e32 v122, 63, v119
	v_sub_u32_e32 v123, 63, v120
	v_lshlrev_b32_e32 v176, 2, v2
	v_lshlrev_b32_e32 v46, 2, v8
	v_add_u32_e32 v124, v9, v7
	v_add_u32_e32 v125, v13, v14
	v_add_u32_e32 v126, v3, v0
	v_add_u32_e32 v127, v16, v17
	v_add_u32_e32 v128, v11, v15
	v_add_u32_e32 v129, v10, v18
	v_add_u32_e32 v130, v10, v1
	v_add_u32_e32 v131, v10, v12
	v_readlane_b32 s3, v253, 28
	s_branch .LBB0_295
.LBB0_294:
	s_add_i32 s28, s28, s44
	s_cmpk_gt_i32 s28, 0xff
	s_cbranch_scc1 .LBB0_303
	s_branch .Lsc_reinit

.LBB0_299:
	s_and_b64 s[34:35], s[26:27], exec
	s_brev_b32 s29, 16
	s_cselect_b32 s30, s29, 0xa000000
	s_add_u32 s33, s80, s30
	s_addc_u32 s34, s81, 0
	s_lshl_b32 s94, s2, 9
	s_lshl_b32 s30, s3, 10
	v_lshl_add_u64 v[48:49], v[26:27], 0, s[94:95]
	s_lshl_b32 s94, s31, 1
	s_lshl_b32 s2, s31, 2
	s_add_u32 s2, s33, s2
	s_addc_u32 s3, s34, 0
	v_lshl_add_u64 v[16:17], s[2:3], 0, v[176:177]
	v_mov_b32_e32 v47, v177
	s_mov_b32 s29, 0
	v_lshl_add_u64 v[50:51], v[28:29], 0, s[94:95]
	v_cndmask_b32_e64 v132, v59, v31, s[26:27]
	v_cndmask_b32_e64 v133, v60, v54, s[26:27]
	v_cndmask_b32_e64 v134, v62, v61, s[26:27]
	v_cndmask_b32_e64 v135, v64, v63, s[26:27]
	v_cndmask_b32_e64 v136, v66, v65, s[26:27]
	v_cndmask_b32_e64 v137, v68, v67, s[26:27]
	v_cndmask_b32_e64 v138, v70, v69, s[26:27]
	v_cndmask_b32_e64 v139, v72, v71, s[26:27]
	v_cndmask_b32_e64 v140, v74, v73, s[26:27]
	v_cndmask_b32_e64 v141, v76, v75, s[26:27]
	v_cndmask_b32_e64 v142, v78, v77, s[26:27]
	v_cndmask_b32_e64 v143, v80, v79, s[26:27]
	v_cndmask_b32_e64 v144, v82, v81, s[26:27]
	v_cndmask_b32_e64 v145, v84, v83, s[26:27]
	v_cndmask_b32_e64 v146, v86, v85, s[26:27]
	v_cndmask_b32_e64 v147, v88, v87, s[26:27]
	v_cndmask_b32_e64 v148, v90, v89, s[26:27]
	v_cndmask_b32_e64 v149, v91, v55, s[26:27]
	v_cndmask_b32_e64 v150, v93, v92, s[26:27]
	v_cndmask_b32_e64 v151, v95, v94, s[26:27]
	v_cndmask_b32_e64 v152, v97, v96, s[26:27]
	v_cndmask_b32_e64 v153, v99, v98, s[26:27]
	v_cndmask_b32_e64 v154, v101, v100, s[26:27]
	v_cndmask_b32_e64 v155, v103, v102, s[26:27]
	v_cndmask_b32_e64 v156, v105, v104, s[26:27]
	v_lshl_add_u64 v[52:53], v[16:17], 0, v[46:47]
	v_cndmask_b32_e64 v47, v121, v118, s[26:27]
	v_cndmask_b32_e64 v157, v122, v119, s[26:27]
	v_cndmask_b32_e64 v158, v123, v120, s[26:27]
	s_movk_i32 s31, 0x3c0
	s_movk_i32 s94, 0x7fff
	s_cmp_lg_u64 s[26:27], 0
	s_cselect_b32 s2, s29, s31
	s_add_i32 s2, s2, s30
	v_add_u32_e32 v236, s2, v133
	v_ashrrev_i32_e32 v237, 31, v236
	v_lshlrev_b64 v[238:239], 10, v[236:237]
	v_lshlrev_b64 v[236:237], 9, v[236:237]
	v_lshl_add_u64 v[238:239], v[48:49], 0, v[238:239]
	v_lshl_add_u64 v[236:237], v[44:45], 0, v[236:237]
	global_load_dword v59, v[238:239], off sc0 sc1
	global_load_ushort v60, v[236:237], off sc0 sc1
	global_load_ushort v61, v[236:237], off offset:256 sc0 sc1
	v_add_u32_e32 v236, s2, v134
	v_ashrrev_i32_e32 v237, 31, v236
	v_lshlrev_b64 v[238:239], 10, v[236:237]
	v_lshlrev_b64 v[236:237], 9, v[236:237]
	v_lshl_add_u64 v[238:239], v[48:49], 0, v[238:239]
	v_lshl_add_u64 v[236:237], v[44:45], 0, v[236:237]
	global_load_dword v62, v[238:239], off sc0 sc1
	global_load_ushort v63, v[236:237], off sc0 sc1
	global_load_ushort v64, v[236:237], off offset:256 sc0 sc1
	v_add_u32_e32 v236, s2, v135
	v_ashrrev_i32_e32 v237, 31, v236
	v_lshlrev_b64 v[238:239], 10, v[236:237]
	v_lshlrev_b64 v[236:237], 9, v[236:237]
	v_lshl_add_u64 v[238:239], v[48:49], 0, v[238:239]
	v_lshl_add_u64 v[236:237], v[44:45], 0, v[236:237]
	global_load_dword v65, v[238:239], off sc0 sc1
	global_load_ushort v66, v[236:237], off sc0 sc1
	global_load_ushort v67, v[236:237], off offset:256 sc0 sc1
	v_add_u32_e32 v236, s2, v136
	v_ashrrev_i32_e32 v237, 31, v236
	v_lshlrev_b64 v[238:239], 10, v[236:237]
	v_lshlrev_b64 v[236:237], 9, v[236:237]
	v_lshl_add_u64 v[238:239], v[48:49], 0, v[238:239]
	v_lshl_add_u64 v[236:237], v[44:45], 0, v[236:237]
	global_load_dword v68, v[238:239], off sc0 sc1
	global_load_ushort v69, v[236:237], off sc0 sc1
	global_load_ushort v70, v[236:237], off offset:256 sc0 sc1
	v_add_u32_e32 v236, s2, v137
	v_ashrrev_i32_e32 v237, 31, v236
	v_lshlrev_b64 v[238:239], 10, v[236:237]
	v_lshlrev_b64 v[236:237], 9, v[236:237]
	v_lshl_add_u64 v[238:239], v[48:49], 0, v[238:239]
	v_lshl_add_u64 v[236:237], v[44:45], 0, v[236:237]
	global_load_dword v71, v[238:239], off sc0 sc1
	global_load_ushort v72, v[236:237], off sc0 sc1
	global_load_ushort v73, v[236:237], off offset:256 sc0 sc1
	v_add_u32_e32 v236, s2, v138
	v_ashrrev_i32_e32 v237, 31, v236
	v_lshlrev_b64 v[238:239], 10, v[236:237]
	v_lshlrev_b64 v[236:237], 9, v[236:237]
	v_lshl_add_u64 v[238:239], v[48:49], 0, v[238:239]
	v_lshl_add_u64 v[236:237], v[44:45], 0, v[236:237]
	global_load_dword v74, v[238:239], off sc0 sc1
	global_load_ushort v75, v[236:237], off sc0 sc1
	global_load_ushort v76, v[236:237], off offset:256 sc0 sc1
	v_add_u32_e32 v236, s2, v139
	v_ashrrev_i32_e32 v237, 31, v236
	v_lshlrev_b64 v[238:239], 10, v[236:237]
	v_lshlrev_b64 v[236:237], 9, v[236:237]
	v_lshl_add_u64 v[238:239], v[48:49], 0, v[238:239]
	v_lshl_add_u64 v[236:237], v[44:45], 0, v[236:237]
	global_load_dword v77, v[238:239], off sc0 sc1
	global_load_ushort v78, v[236:237], off sc0 sc1
	global_load_ushort v79, v[236:237], off offset:256 sc0 sc1
	v_add_u32_e32 v236, s2, v140
	v_ashrrev_i32_e32 v237, 31, v236
	v_lshlrev_b64 v[238:239], 10, v[236:237]
	v_lshlrev_b64 v[236:237], 9, v[236:237]
	v_lshl_add_u64 v[238:239], v[48:49], 0, v[238:239]
	v_lshl_add_u64 v[236:237], v[44:45], 0, v[236:237]
	global_load_dword v80, v[238:239], off sc0 sc1
	global_load_ushort v81, v[236:237], off sc0 sc1
	global_load_ushort v82, v[236:237], off offset:256 sc0 sc1
	v_add_u32_e32 v236, s2, v141
	v_ashrrev_i32_e32 v237, 31, v236
	v_lshlrev_b64 v[238:239], 10, v[236:237]
	v_lshlrev_b64 v[236:237], 9, v[236:237]
	v_lshl_add_u64 v[238:239], v[48:49], 0, v[238:239]
	v_lshl_add_u64 v[236:237], v[44:45], 0, v[236:237]
	global_load_dword v83, v[238:239], off sc0 sc1
	global_load_ushort v84, v[236:237], off sc0 sc1
	global_load_ushort v85, v[236:237], off offset:256 sc0 sc1
	v_add_u32_e32 v236, s2, v142
	v_ashrrev_i32_e32 v237, 31, v236
	v_lshlrev_b64 v[238:239], 10, v[236:237]
	v_lshlrev_b64 v[236:237], 9, v[236:237]
	v_lshl_add_u64 v[238:239], v[48:49], 0, v[238:239]
	v_lshl_add_u64 v[236:237], v[44:45], 0, v[236:237]
	global_load_dword v86, v[238:239], off sc0 sc1
	global_load_ushort v87, v[236:237], off sc0 sc1
	global_load_ushort v88, v[236:237], off offset:256 sc0 sc1
	v_add_u32_e32 v236, s2, v143
	v_ashrrev_i32_e32 v237, 31, v236
	v_lshlrev_b64 v[238:239], 10, v[236:237]
	v_lshlrev_b64 v[236:237], 9, v[236:237]
	v_lshl_add_u64 v[238:239], v[48:49], 0, v[238:239]
	v_lshl_add_u64 v[236:237], v[44:45], 0, v[236:237]
	global_load_dword v89, v[238:239], off sc0 sc1
	global_load_ushort v90, v[236:237], off sc0 sc1
	global_load_ushort v91, v[236:237], off offset:256 sc0 sc1
	v_add_u32_e32 v236, s2, v144
	v_ashrrev_i32_e32 v237, 31, v236
	v_lshlrev_b64 v[238:239], 10, v[236:237]
	v_lshlrev_b64 v[236:237], 9, v[236:237]
	v_lshl_add_u64 v[238:239], v[48:49], 0, v[238:239]
	v_lshl_add_u64 v[236:237], v[44:45], 0, v[236:237]
	global_load_dword v92, v[238:239], off sc0 sc1
	global_load_ushort v93, v[236:237], off sc0 sc1
	global_load_ushort v94, v[236:237], off offset:256 sc0 sc1
	v_add_u32_e32 v236, s2, v145
	v_ashrrev_i32_e32 v237, 31, v236
	v_lshlrev_b64 v[238:239], 10, v[236:237]
	v_lshlrev_b64 v[236:237], 9, v[236:237]
	v_lshl_add_u64 v[238:239], v[48:49], 0, v[238:239]
	v_lshl_add_u64 v[236:237], v[44:45], 0, v[236:237]
	global_load_dword v95, v[238:239], off sc0 sc1
	global_load_ushort v96, v[236:237], off sc0 sc1
	global_load_ushort v97, v[236:237], off offset:256 sc0 sc1
	v_add_u32_e32 v236, s2, v146
	v_ashrrev_i32_e32 v237, 31, v236
	v_lshlrev_b64 v[238:239], 10, v[236:237]
	v_lshlrev_b64 v[236:237], 9, v[236:237]
	v_lshl_add_u64 v[238:239], v[48:49], 0, v[238:239]
	v_lshl_add_u64 v[236:237], v[44:45], 0, v[236:237]
	global_load_dword v98, v[238:239], off sc0 sc1
	global_load_ushort v99, v[236:237], off sc0 sc1
	global_load_ushort v100, v[236:237], off offset:256 sc0 sc1
	v_add_u32_e32 v236, s2, v147
	v_ashrrev_i32_e32 v237, 31, v236
	v_lshlrev_b64 v[238:239], 10, v[236:237]
	v_lshlrev_b64 v[236:237], 9, v[236:237]
	v_lshl_add_u64 v[238:239], v[48:49], 0, v[238:239]
	v_lshl_add_u64 v[236:237], v[44:45], 0, v[236:237]
	global_load_dword v101, v[238:239], off sc0 sc1
	global_load_ushort v102, v[236:237], off sc0 sc1
	global_load_ushort v103, v[236:237], off offset:256 sc0 sc1
	v_add_u32_e32 v236, s2, v148
	v_ashrrev_i32_e32 v237, 31, v236
	v_lshlrev_b64 v[238:239], 10, v[236:237]
	v_lshlrev_b64 v[236:237], 9, v[236:237]
	v_lshl_add_u64 v[238:239], v[48:49], 0, v[238:239]
	v_lshl_add_u64 v[236:237], v[44:45], 0, v[236:237]
	global_load_dword v104, v[238:239], off sc0 sc1
	global_load_ushort v105, v[236:237], off sc0 sc1
	global_load_ushort v227, v[236:237], off offset:256 sc0 sc1
	v_add_u32_e32 v236, s2, v149
	v_ashrrev_i32_e32 v237, 31, v236
	v_lshlrev_b64 v[236:237], 9, v[236:237]
	v_lshl_add_u64 v[236:237], v[50:51], 0, v[236:237]
	global_load_ushort v228, v[236:237], off sc0 sc1
	v_add_u32_e32 v236, s2, v150
	v_ashrrev_i32_e32 v237, 31, v236
	v_lshlrev_b64 v[236:237], 9, v[236:237]
	v_lshl_add_u64 v[236:237], v[50:51], 0, v[236:237]
	global_load_ushort v229, v[236:237], off sc0 sc1
	v_add_u32_e32 v236, s2, v151
	v_ashrrev_i32_e32 v237, 31, v236
	v_lshlrev_b64 v[236:237], 9, v[236:237]
	v_lshl_add_u64 v[236:237], v[50:51], 0, v[236:237]
	global_load_ushort v230, v[236:237], off sc0 sc1
	v_add_u32_e32 v236, s2, v152
	v_ashrrev_i32_e32 v237, 31, v236
	v_lshlrev_b64 v[236:237], 9, v[236:237]
	v_lshl_add_u64 v[236:237], v[50:51], 0, v[236:237]
	global_load_ushort v231, v[236:237], off sc0 sc1
	v_add_u32_e32 v236, s2, v153
	v_ashrrev_i32_e32 v237, 31, v236
	v_lshlrev_b64 v[236:237], 9, v[236:237]
	v_lshl_add_u64 v[236:237], v[50:51], 0, v[236:237]
	global_load_ushort v232, v[236:237], off sc0 sc1
	v_add_u32_e32 v236, s2, v154
	v_ashrrev_i32_e32 v237, 31, v236
	v_lshlrev_b64 v[236:237], 9, v[236:237]
	v_lshl_add_u64 v[236:237], v[50:51], 0, v[236:237]
	global_load_ushort v233, v[236:237], off sc0 sc1
	v_add_u32_e32 v236, s2, v155
	v_ashrrev_i32_e32 v237, 31, v236
	v_lshlrev_b64 v[236:237], 9, v[236:237]
	v_lshl_add_u64 v[236:237], v[50:51], 0, v[236:237]
	global_load_ushort v234, v[236:237], off sc0 sc1
	v_add_u32_e32 v236, s2, v156
	v_ashrrev_i32_e32 v237, 31, v236
	v_lshlrev_b64 v[236:237], 9, v[236:237]
	v_lshl_add_u64 v[236:237], v[50:51], 0, v[236:237]
	global_load_ushort v235, v[236:237], off sc0 sc1
	s_waitcnt vmcnt(0)
	s_branch .LBB0_301

.LBB0_301:
	s_and_b64 s[2:3], s[26:27], exec
	s_cselect_b32 s33, s29, s31
	s_add_i32 s33, s33, s30
	s_waitcnt vmcnt(8)
	v_mov_b32_e32 v23, v59
	v_mov_b32_e32 v161, v60
	v_mov_b32_e32 v162, v61
	v_mov_b32_e32 v20, v62
	v_mov_b32_e32 v163, v63
	v_mov_b32_e32 v164, v64
	v_mov_b32_e32 v21, v65
	v_mov_b32_e32 v167, v66
	v_mov_b32_e32 v168, v67
	v_mov_b32_e32 v22, v68
	v_mov_b32_e32 v169, v69
	v_mov_b32_e32 v170, v70
	v_mov_b32_e32 v159, v71
	v_mov_b32_e32 v171, v72
	v_mov_b32_e32 v172, v73
	v_mov_b32_e32 v160, v74
	v_mov_b32_e32 v173, v75
	v_mov_b32_e32 v174, v76
	v_mov_b32_e32 v165, v77
	v_mov_b32_e32 v183, v78
	v_mov_b32_e32 v184, v79
	v_mov_b32_e32 v166, v80
	v_mov_b32_e32 v185, v81
	v_mov_b32_e32 v186, v82
	v_mov_b32_e32 v175, v83
	v_mov_b32_e32 v187, v84
	v_mov_b32_e32 v188, v85
	v_mov_b32_e32 v182, v86
	v_mov_b32_e32 v189, v87
	v_mov_b32_e32 v190, v88
	v_mov_b32_e32 v221, v89
	v_mov_b32_e32 v193, v90
	v_mov_b32_e32 v194, v91
	v_mov_b32_e32 v222, v92
	v_mov_b32_e32 v195, v93
	v_mov_b32_e32 v196, v94
	v_mov_b32_e32 v223, v95
	v_mov_b32_e32 v197, v96
	v_mov_b32_e32 v198, v97
	v_mov_b32_e32 v224, v98
	v_mov_b32_e32 v199, v99
	v_mov_b32_e32 v200, v100
	v_mov_b32_e32 v225, v101
	v_mov_b32_e32 v214, v102
	v_mov_b32_e32 v215, v103
	v_mov_b32_e32 v226, v104
	v_mov_b32_e32 v216, v105
	v_mov_b32_e32 v217, v227
	v_mov_b32_e32 v18, v228
	v_mov_b32_e32 v19, v229
	v_mov_b32_e32 v191, v230
	v_mov_b32_e32 v192, v231
	v_mov_b32_e32 v201, v232
	v_mov_b32_e32 v213, v233
	v_mov_b32_e32 v218, v234
	v_mov_b32_e32 v16, v235
	s_cmp_eq_u32 s31, 0
	s_cbranch_scc1 .Lsc_nopf
	s_add_i32 s2, s29, 64
	s_sub_i32 s3, s31, 64
	s_cmp_lg_u64 s[26:27], 0
	s_cselect_b32 s2, s2, s3
	s_add_i32 s2, s2, s30
	v_add_u32_e32 v236, s2, v133
	v_ashrrev_i32_e32 v237, 31, v236
	v_lshlrev_b64 v[238:239], 10, v[236:237]
	v_lshlrev_b64 v[236:237], 9, v[236:237]
	v_lshl_add_u64 v[238:239], v[48:49], 0, v[238:239]
	v_lshl_add_u64 v[236:237], v[44:45], 0, v[236:237]
	global_load_dword v59, v[238:239], off sc0 sc1
	global_load_ushort v60, v[236:237], off sc0 sc1
	global_load_ushort v61, v[236:237], off offset:256 sc0 sc1
	v_add_u32_e32 v236, s2, v134
	v_ashrrev_i32_e32 v237, 31, v236
	v_lshlrev_b64 v[238:239], 10, v[236:237]
	v_lshlrev_b64 v[236:237], 9, v[236:237]
	v_lshl_add_u64 v[238:239], v[48:49], 0, v[238:239]
	v_lshl_add_u64 v[236:237], v[44:45], 0, v[236:237]
	global_load_dword v62, v[238:239], off sc0 sc1
	global_load_ushort v63, v[236:237], off sc0 sc1
	global_load_ushort v64, v[236:237], off offset:256 sc0 sc1
	v_add_u32_e32 v236, s2, v135
	v_ashrrev_i32_e32 v237, 31, v236
	v_lshlrev_b64 v[238:239], 10, v[236:237]
	v_lshlrev_b64 v[236:237], 9, v[236:237]
	v_lshl_add_u64 v[238:239], v[48:49], 0, v[238:239]
	v_lshl_add_u64 v[236:237], v[44:45], 0, v[236:237]
	global_load_dword v65, v[238:239], off sc0 sc1
	global_load_ushort v66, v[236:237], off sc0 sc1
	global_load_ushort v67, v[236:237], off offset:256 sc0 sc1
	v_add_u32_e32 v236, s2, v136
	v_ashrrev_i32_e32 v237, 31, v236
	v_lshlrev_b64 v[238:239], 10, v[236:237]
	v_lshlrev_b64 v[236:237], 9, v[236:237]
	v_lshl_add_u64 v[238:239], v[48:49], 0, v[238:239]
	v_lshl_add_u64 v[236:237], v[44:45], 0, v[236:237]
	global_load_dword v68, v[238:239], off sc0 sc1
	global_load_ushort v69, v[236:237], off sc0 sc1
	global_load_ushort v70, v[236:237], off offset:256 sc0 sc1
	v_add_u32_e32 v236, s2, v137
	v_ashrrev_i32_e32 v237, 31, v236
	v_lshlrev_b64 v[238:239], 10, v[236:237]
	v_lshlrev_b64 v[236:237], 9, v[236:237]
	v_lshl_add_u64 v[238:239], v[48:49], 0, v[238:239]
	v_lshl_add_u64 v[236:237], v[44:45], 0, v[236:237]
	global_load_dword v71, v[238:239], off sc0 sc1
	global_load_ushort v72, v[236:237], off sc0 sc1
	global_load_ushort v73, v[236:237], off offset:256 sc0 sc1
	v_add_u32_e32 v236, s2, v138
	v_ashrrev_i32_e32 v237, 31, v236
	v_lshlrev_b64 v[238:239], 10, v[236:237]
	v_lshlrev_b64 v[236:237], 9, v[236:237]
	v_lshl_add_u64 v[238:239], v[48:49], 0, v[238:239]
	v_lshl_add_u64 v[236:237], v[44:45], 0, v[236:237]
	global_load_dword v74, v[238:239], off sc0 sc1
	global_load_ushort v75, v[236:237], off sc0 sc1
	global_load_ushort v76, v[236:237], off offset:256 sc0 sc1
	v_add_u32_e32 v236, s2, v139
	v_ashrrev_i32_e32 v237, 31, v236
	v_lshlrev_b64 v[238:239], 10, v[236:237]
	v_lshlrev_b64 v[236:237], 9, v[236:237]
	v_lshl_add_u64 v[238:239], v[48:49], 0, v[238:239]
	v_lshl_add_u64 v[236:237], v[44:45], 0, v[236:237]
	global_load_dword v77, v[238:239], off sc0 sc1
	global_load_ushort v78, v[236:237], off sc0 sc1
	global_load_ushort v79, v[236:237], off offset:256 sc0 sc1
	v_add_u32_e32 v236, s2, v140
	v_ashrrev_i32_e32 v237, 31, v236
	v_lshlrev_b64 v[238:239], 10, v[236:237]
	v_lshlrev_b64 v[236:237], 9, v[236:237]
	v_lshl_add_u64 v[238:239], v[48:49], 0, v[238:239]
	v_lshl_add_u64 v[236:237], v[44:45], 0, v[236:237]
	global_load_dword v80, v[238:239], off sc0 sc1
	global_load_ushort v81, v[236:237], off sc0 sc1
	global_load_ushort v82, v[236:237], off offset:256 sc0 sc1
	v_add_u32_e32 v236, s2, v141
	v_ashrrev_i32_e32 v237, 31, v236
	v_lshlrev_b64 v[238:239], 10, v[236:237]
	v_lshlrev_b64 v[236:237], 9, v[236:237]
	v_lshl_add_u64 v[238:239], v[48:49], 0, v[238:239]
	v_lshl_add_u64 v[236:237], v[44:45], 0, v[236:237]
	global_load_dword v83, v[238:239], off sc0 sc1
	global_load_ushort v84, v[236:237], off sc0 sc1
	global_load_ushort v85, v[236:237], off offset:256 sc0 sc1
	v_add_u32_e32 v236, s2, v142
	v_ashrrev_i32_e32 v237, 31, v236
	v_lshlrev_b64 v[238:239], 10, v[236:237]
	v_lshlrev_b64 v[236:237], 9, v[236:237]
	v_lshl_add_u64 v[238:239], v[48:49], 0, v[238:239]
	v_lshl_add_u64 v[236:237], v[44:45], 0, v[236:237]
	global_load_dword v86, v[238:239], off sc0 sc1
	global_load_ushort v87, v[236:237], off sc0 sc1
	global_load_ushort v88, v[236:237], off offset:256 sc0 sc1
	v_add_u32_e32 v236, s2, v143
	v_ashrrev_i32_e32 v237, 31, v236
	v_lshlrev_b64 v[238:239], 10, v[236:237]
	v_lshlrev_b64 v[236:237], 9, v[236:237]
	v_lshl_add_u64 v[238:239], v[48:49], 0, v[238:239]
	v_lshl_add_u64 v[236:237], v[44:45], 0, v[236:237]
	global_load_dword v89, v[238:239], off sc0 sc1
	global_load_ushort v90, v[236:237], off sc0 sc1
	global_load_ushort v91, v[236:237], off offset:256 sc0 sc1
	v_add_u32_e32 v236, s2, v144
	v_ashrrev_i32_e32 v237, 31, v236
	v_lshlrev_b64 v[238:239], 10, v[236:237]
	v_lshlrev_b64 v[236:237], 9, v[236:237]
	v_lshl_add_u64 v[238:239], v[48:49], 0, v[238:239]
	v_lshl_add_u64 v[236:237], v[44:45], 0, v[236:237]
	global_load_dword v92, v[238:239], off sc0 sc1
	global_load_ushort v93, v[236:237], off sc0 sc1
	global_load_ushort v94, v[236:237], off offset:256 sc0 sc1
	v_add_u32_e32 v236, s2, v145
	v_ashrrev_i32_e32 v237, 31, v236
	v_lshlrev_b64 v[238:239], 10, v[236:237]
	v_lshlrev_b64 v[236:237], 9, v[236:237]
	v_lshl_add_u64 v[238:239], v[48:49], 0, v[238:239]
	v_lshl_add_u64 v[236:237], v[44:45], 0, v[236:237]
	global_load_dword v95, v[238:239], off sc0 sc1
	global_load_ushort v96, v[236:237], off sc0 sc1
	global_load_ushort v97, v[236:237], off offset:256 sc0 sc1
	v_add_u32_e32 v236, s2, v146
	v_ashrrev_i32_e32 v237, 31, v236
	v_lshlrev_b64 v[238:239], 10, v[236:237]
	v_lshlrev_b64 v[236:237], 9, v[236:237]
	v_lshl_add_u64 v[238:239], v[48:49], 0, v[238:239]
	v_lshl_add_u64 v[236:237], v[44:45], 0, v[236:237]
	global_load_dword v98, v[238:239], off sc0 sc1
	global_load_ushort v99, v[236:237], off sc0 sc1
	global_load_ushort v100, v[236:237], off offset:256 sc0 sc1
	v_add_u32_e32 v236, s2, v147
	v_ashrrev_i32_e32 v237, 31, v236
	v_lshlrev_b64 v[238:239], 10, v[236:237]
	v_lshlrev_b64 v[236:237], 9, v[236:237]
	v_lshl_add_u64 v[238:239], v[48:49], 0, v[238:239]
	v_lshl_add_u64 v[236:237], v[44:45], 0, v[236:237]
	global_load_dword v101, v[238:239], off sc0 sc1
	global_load_ushort v102, v[236:237], off sc0 sc1
	global_load_ushort v103, v[236:237], off offset:256 sc0 sc1
	v_add_u32_e32 v236, s2, v148
	v_ashrrev_i32_e32 v237, 31, v236
	v_lshlrev_b64 v[238:239], 10, v[236:237]
	v_lshlrev_b64 v[236:237], 9, v[236:237]
	v_lshl_add_u64 v[238:239], v[48:49], 0, v[238:239]
	v_lshl_add_u64 v[236:237], v[44:45], 0, v[236:237]
	global_load_dword v104, v[238:239], off sc0 sc1
	global_load_ushort v105, v[236:237], off sc0 sc1
	global_load_ushort v227, v[236:237], off offset:256 sc0 sc1
	v_add_u32_e32 v236, s2, v149
	v_ashrrev_i32_e32 v237, 31, v236
	v_lshlrev_b64 v[236:237], 9, v[236:237]
	v_lshl_add_u64 v[236:237], v[50:51], 0, v[236:237]
	global_load_ushort v228, v[236:237], off sc0 sc1
	v_add_u32_e32 v236, s2, v150
	v_ashrrev_i32_e32 v237, 31, v236
	v_lshlrev_b64 v[236:237], 9, v[236:237]
	v_lshl_add_u64 v[236:237], v[50:51], 0, v[236:237]
	global_load_ushort v229, v[236:237], off sc0 sc1
	v_add_u32_e32 v236, s2, v151
	v_ashrrev_i32_e32 v237, 31, v236
	v_lshlrev_b64 v[236:237], 9, v[236:237]
	v_lshl_add_u64 v[236:237], v[50:51], 0, v[236:237]
	global_load_ushort v230, v[236:237], off sc0 sc1
	v_add_u32_e32 v236, s2, v152
	v_ashrrev_i32_e32 v237, 31, v236
	v_lshlrev_b64 v[236:237], 9, v[236:237]
	v_lshl_add_u64 v[236:237], v[50:51], 0, v[236:237]
	global_load_ushort v231, v[236:237], off sc0 sc1
	v_add_u32_e32 v236, s2, v153
	v_ashrrev_i32_e32 v237, 31, v236
	v_lshlrev_b64 v[236:237], 9, v[236:237]
	v_lshl_add_u64 v[236:237], v[50:51], 0, v[236:237]
	global_load_ushort v232, v[236:237], off sc0 sc1
	v_add_u32_e32 v236, s2, v154
	v_ashrrev_i32_e32 v237, 31, v236
	v_lshlrev_b64 v[236:237], 9, v[236:237]
	v_lshl_add_u64 v[236:237], v[50:51], 0, v[236:237]
	global_load_ushort v233, v[236:237], off sc0 sc1
	v_add_u32_e32 v236, s2, v155
	v_ashrrev_i32_e32 v237, 31, v236
	v_lshlrev_b64 v[236:237], 9, v[236:237]
	v_lshl_add_u64 v[236:237], v[50:51], 0, v[236:237]
	global_load_ushort v234, v[236:237], off sc0 sc1
	v_add_u32_e32 v236, s2, v156
	v_ashrrev_i32_e32 v237, 31, v236
	v_lshlrev_b64 v[236:237], 9, v[236:237]
	v_lshl_add_u64 v[236:237], v[50:51], 0, v[236:237]
	global_load_ushort v235, v[236:237], off sc0 sc1
.Lsc_nopf:
	v_add_f32_e32 v220, v23, v20
	v_lshlrev_b32_e32 v17, 16, v18
	v_lshlrev_b32_e32 v18, 16, v19
	v_lshlrev_b32_e32 v19, 16, v191
	v_lshlrev_b32_e32 v191, 16, v192
	v_lshlrev_b32_e32 v192, 16, v201
	v_lshlrev_b32_e32 v201, 16, v213
	v_lshlrev_b32_e32 v213, 16, v218
	v_lshlrev_b32_e32 v218, 16, v16
	v_cvt_pk_bf16_f32 v16, v17, v18
	v_cvt_pk_bf16_f32 v17, v19, v191
	v_cvt_pk_bf16_f32 v18, v192, v201
	v_cvt_pk_bf16_f32 v19, v213, v218
	v_add_f32_e32 v218, v220, v21
	v_add_f32_e32 v219, v218, v22
	v_add_f32_e32 v201, v219, v159
	v_add_f32_e32 v213, v201, v160
	v_add_f32_e32 v191, v213, v165
	v_add_f32_e32 v192, v191, v166
	v_add_f32_e32 v175, v192, v175
	v_add_f32_e32 v182, v175, v182
	v_add_f32_e32 v165, v182, v221
	v_add_f32_e32 v166, v165, v222
	v_add_f32_e32 v159, v166, v223
	v_add_f32_e32 v160, v159, v224
	v_add_f32_e32 v21, v160, v225
	v_add_f32_e32 v22, v21, v226
	ds_write_b32 v56, v22
	ds_write_b128 v124, v[16:19] offset:53248
	s_waitcnt lgkmcnt(0)
	s_barrier
	ds_read2st64_b32 v[18:19], v57 offset1:2
	ds_read2st64_b32 v[16:17], v57 offset0:4 offset1:6
	s_waitcnt lgkmcnt(1)
	v_add_f32_e32 v18, 0, v18
	v_add_f32_e32 v20, v18, v19
	s_waitcnt lgkmcnt(0)
	v_add_f32_e32 v20, v20, v16
	v_add_f32_e32 v20, v20, v17
	v_mul_f32_e32 v20, 0x3fb8aa3b, v20
	v_exp_f32_e32 v20, v20
	s_and_saveexec_b64 s[2:3], vcc
	s_cbranch_execz .LBB0_300
	ds_write_b32 v58, v20
	s_branch .LBB0_300

.LBB0_309:
	s_ashr_i32 s20, s18, 3
	s_and_b32 s19, s18, 3
	s_bfe_u32 s21, s18, 0x10002
	s_cmp_eq_u32 s21, 0
	s_cselect_b64 s[14:15], -1, 0
	s_lshl_b32 s94, s21, 9
	v_lshl_add_u64 v[38:39], v[20:21], 0, s[94:95]
	s_lshl_b32 s94, s19, 7
	v_mov_b32_e32 v96, 0
	s_mov_b32 s23, 0
	s_lshl_b32 s24, s20, 10
	s_lshl_b32 s22, s19, 6
	v_cndmask_b32_e64 v37, v25, v42, s[14:15]
	v_cndmask_b32_e64 v97, v48, v47, s[14:15]
	v_cndmask_b32_e64 v98, v50, v49, s[14:15]
	v_cndmask_b32_e64 v99, v52, v51, s[14:15]
	v_cndmask_b32_e64 v100, v54, v53, s[14:15]
	v_cndmask_b32_e64 v101, v56, v55, s[14:15]
	v_cndmask_b32_e64 v102, v58, v57, s[14:15]
	v_cndmask_b32_e64 v103, v60, v59, s[14:15]
	v_cndmask_b32_e64 v104, v62, v61, s[14:15]
	v_cndmask_b32_e64 v105, v64, v63, s[14:15]
	v_cndmask_b32_e64 v106, v66, v65, s[14:15]
	v_cndmask_b32_e64 v107, v68, v67, s[14:15]
	v_cndmask_b32_e64 v108, v70, v69, s[14:15]
	v_cndmask_b32_e64 v109, v72, v71, s[14:15]
	v_cndmask_b32_e64 v110, v74, v73, s[14:15]
	v_cndmask_b32_e64 v111, v76, v75, s[14:15]
	v_cndmask_b32_e64 v112, v77, v43, s[14:15]
	v_cndmask_b32_e64 v113, v79, v78, s[14:15]
	v_cndmask_b32_e64 v114, v81, v80, s[14:15]
	v_cndmask_b32_e64 v115, v83, v82, s[14:15]
	v_cndmask_b32_e64 v116, v85, v84, s[14:15]
	s_movk_i32 s25, 0x3c0
	v_mov_b32_e32 v0, 0
	v_mov_b32_e32 v1, v96
	v_mov_b32_e32 v2, v96
	v_mov_b32_e32 v3, v96
	v_mov_b32_e32 v4, 0
	v_mov_b32_e32 v5, v96
	v_mov_b32_e32 v6, v96
	v_mov_b32_e32 v7, v96
	v_mov_b32_e32 v8, 0
	v_mov_b32_e32 v9, v96
	v_mov_b32_e32 v10, v96
	v_mov_b32_e32 v11, v96
	v_mov_b32_e32 v12, 0
	v_mov_b32_e32 v13, v96
	v_mov_b32_e32 v14, v96
	v_mov_b32_e32 v15, v96
	v_cndmask_b32_e64 v117, v87, v86, s[14:15]
	v_cndmask_b32_e64 v118, v89, v88, s[14:15]
	v_cndmask_b32_e64 v119, v91, v90, s[14:15]
	v_lshl_add_u64 v[40:41], v[22:23], 0, s[94:95]
	s_mov_b32 s26, 0xc988000
	s_and_b64 s[2:3], s[14:15], exec
	s_cselect_b32 s2, s23, s25
	s_add_i32 s2, s2, s24
	v_add_u32_e32 v236, s2, v37
	v_ashrrev_i32_e32 v237, 31, v236
	v_lshlrev_b64 v[238:239], 10, v[236:237]
	v_lshlrev_b64 v[236:237], 9, v[236:237]
	v_lshl_add_u64 v[236:237], s[46:47], 0, v[236:237]
	v_lshl_add_u64 v[236:237], v[236:237], 0, v[176:177]
	v_add_co_u32_e64 v236, s[16:17], s26, v236
	v_lshl_add_u64 v[238:239], v[38:39], 0, v[238:239]
	s_nop 0
	v_addc_co_u32_e64 v237, s[16:17], 0, v237, s[16:17]
	global_load_dword v159, v[238:239], off sc0 sc1
	global_load_ushort v160, v[236:237], off offset:256 sc0 sc1
	v_add_u32_e32 v236, s2, v97
	v_ashrrev_i32_e32 v237, 31, v236
	v_lshlrev_b64 v[238:239], 10, v[236:237]
	v_lshlrev_b64 v[236:237], 9, v[236:237]
	v_lshl_add_u64 v[236:237], s[46:47], 0, v[236:237]
	v_lshl_add_u64 v[236:237], v[236:237], 0, v[176:177]
	v_add_co_u32_e64 v236, s[16:17], s26, v236
	v_lshl_add_u64 v[238:239], v[38:39], 0, v[238:239]
	s_nop 0
	v_addc_co_u32_e64 v237, s[16:17], 0, v237, s[16:17]
	global_load_dword v161, v[238:239], off sc0 sc1
	global_load_ushort v162, v[236:237], off offset:256 sc0 sc1
	v_add_u32_e32 v236, s2, v98
	v_ashrrev_i32_e32 v237, 31, v236
	v_lshlrev_b64 v[238:239], 10, v[236:237]
	v_lshlrev_b64 v[236:237], 9, v[236:237]
	v_lshl_add_u64 v[236:237], s[46:47], 0, v[236:237]
	v_lshl_add_u64 v[236:237], v[236:237], 0, v[176:177]
	v_add_co_u32_e64 v236, s[16:17], s26, v236
	v_lshl_add_u64 v[238:239], v[38:39], 0, v[238:239]
	s_nop 0
	v_addc_co_u32_e64 v237, s[16:17], 0, v237, s[16:17]
	global_load_dword v163, v[238:239], off sc0 sc1
	global_load_ushort v164, v[236:237], off offset:256 sc0 sc1
	v_add_u32_e32 v236, s2, v99
	v_ashrrev_i32_e32 v237, 31, v236
	v_lshlrev_b64 v[238:239], 10, v[236:237]
	v_lshlrev_b64 v[236:237], 9, v[236:237]
	v_lshl_add_u64 v[236:237], s[46:47], 0, v[236:237]
	v_lshl_add_u64 v[236:237], v[236:237], 0, v[176:177]
	v_add_co_u32_e64 v236, s[16:17], s26, v236
	v_lshl_add_u64 v[238:239], v[38:39], 0, v[238:239]
	s_nop 0
	v_addc_co_u32_e64 v237, s[16:17], 0, v237, s[16:17]
	global_load_dword v165, v[238:239], off sc0 sc1
	global_load_ushort v166, v[236:237], off offset:256 sc0 sc1
	v_add_u32_e32 v236, s2, v100
	v_ashrrev_i32_e32 v237, 31, v236
	v_lshlrev_b64 v[238:239], 10, v[236:237]
	v_lshlrev_b64 v[236:237], 9, v[236:237]
	v_lshl_add_u64 v[236:237], s[46:47], 0, v[236:237]
	v_lshl_add_u64 v[236:237], v[236:237], 0, v[176:177]
	v_add_co_u32_e64 v236, s[16:17], s26, v236
	v_lshl_add_u64 v[238:239], v[38:39], 0, v[238:239]
	s_nop 0
	v_addc_co_u32_e64 v237, s[16:17], 0, v237, s[16:17]
	global_load_dword v167, v[238:239], off sc0 sc1
	global_load_ushort v168, v[236:237], off offset:256 sc0 sc1
	v_add_u32_e32 v236, s2, v101
	v_ashrrev_i32_e32 v237, 31, v236
	v_lshlrev_b64 v[238:239], 10, v[236:237]
	v_lshlrev_b64 v[236:237], 9, v[236:237]
	v_lshl_add_u64 v[236:237], s[46:47], 0, v[236:237]
	v_lshl_add_u64 v[236:237], v[236:237], 0, v[176:177]
	v_add_co_u32_e64 v236, s[16:17], s26, v236
	v_lshl_add_u64 v[238:239], v[38:39], 0, v[238:239]
	s_nop 0
	v_addc_co_u32_e64 v237, s[16:17], 0, v237, s[16:17]
	global_load_dword v169, v[238:239], off sc0 sc1
	global_load_ushort v170, v[236:237], off offset:256 sc0 sc1
	v_add_u32_e32 v236, s2, v102
	v_ashrrev_i32_e32 v237, 31, v236
	v_lshlrev_b64 v[238:239], 10, v[236:237]
	v_lshlrev_b64 v[236:237], 9, v[236:237]
	v_lshl_add_u64 v[236:237], s[46:47], 0, v[236:237]
	v_lshl_add_u64 v[236:237], v[236:237], 0, v[176:177]
	v_add_co_u32_e64 v236, s[16:17], s26, v236
	v_lshl_add_u64 v[238:239], v[38:39], 0, v[238:239]
	s_nop 0
	v_addc_co_u32_e64 v237, s[16:17], 0, v237, s[16:17]
	global_load_dword v171, v[238:239], off sc0 sc1
	global_load_ushort v172, v[236:237], off offset:256 sc0 sc1
	v_add_u32_e32 v236, s2, v103
	v_ashrrev_i32_e32 v237, 31, v236
	v_lshlrev_b64 v[238:239], 10, v[236:237]
	v_lshlrev_b64 v[236:237], 9, v[236:237]
	v_lshl_add_u64 v[236:237], s[46:47], 0, v[236:237]
	v_lshl_add_u64 v[236:237], v[236:237], 0, v[176:177]
	v_add_co_u32_e64 v236, s[16:17], s26, v236
	v_lshl_add_u64 v[238:239], v[38:39], 0, v[238:239]
	s_nop 0
	v_addc_co_u32_e64 v237, s[16:17], 0, v237, s[16:17]
	global_load_dword v173, v[238:239], off sc0 sc1
	global_load_ushort v174, v[236:237], off offset:256 sc0 sc1
	v_add_u32_e32 v236, s2, v104
	v_ashrrev_i32_e32 v237, 31, v236
	v_lshlrev_b64 v[238:239], 10, v[236:237]
	v_lshlrev_b64 v[236:237], 9, v[236:237]
	v_lshl_add_u64 v[236:237], s[46:47], 0, v[236:237]
	v_lshl_add_u64 v[236:237], v[236:237], 0, v[176:177]
	v_add_co_u32_e64 v236, s[16:17], s26, v236
	v_lshl_add_u64 v[238:239], v[38:39], 0, v[238:239]
	s_nop 0
	v_addc_co_u32_e64 v237, s[16:17], 0, v237, s[16:17]
	global_load_dword v175, v[238:239], off sc0 sc1
	global_load_ushort v182, v[236:237], off offset:256 sc0 sc1
	v_add_u32_e32 v236, s2, v105
	v_ashrrev_i32_e32 v237, 31, v236
	v_lshlrev_b64 v[238:239], 10, v[236:237]
	v_lshlrev_b64 v[236:237], 9, v[236:237]
	v_lshl_add_u64 v[236:237], s[46:47], 0, v[236:237]
	v_lshl_add_u64 v[236:237], v[236:237], 0, v[176:177]
	v_add_co_u32_e64 v236, s[16:17], s26, v236
	v_lshl_add_u64 v[238:239], v[38:39], 0, v[238:239]
	s_nop 0
	v_addc_co_u32_e64 v237, s[16:17], 0, v237, s[16:17]
	global_load_dword v183, v[238:239], off sc0 sc1
	global_load_ushort v184, v[236:237], off offset:256 sc0 sc1
	v_add_u32_e32 v236, s2, v106
	v_ashrrev_i32_e32 v237, 31, v236
	v_lshlrev_b64 v[238:239], 10, v[236:237]
	v_lshlrev_b64 v[236:237], 9, v[236:237]
	v_lshl_add_u64 v[236:237], s[46:47], 0, v[236:237]
	v_lshl_add_u64 v[236:237], v[236:237], 0, v[176:177]
	v_add_co_u32_e64 v236, s[16:17], s26, v236
	v_lshl_add_u64 v[238:239], v[38:39], 0, v[238:239]
	s_nop 0
	v_addc_co_u32_e64 v237, s[16:17], 0, v237, s[16:17]
	global_load_dword v185, v[238:239], off sc0 sc1
	global_load_ushort v186, v[236:237], off offset:256 sc0 sc1
	v_add_u32_e32 v236, s2, v107
	v_ashrrev_i32_e32 v237, 31, v236
	v_lshlrev_b64 v[238:239], 10, v[236:237]
	v_lshlrev_b64 v[236:237], 9, v[236:237]
	v_lshl_add_u64 v[236:237], s[46:47], 0, v[236:237]
	v_lshl_add_u64 v[236:237], v[236:237], 0, v[176:177]
	v_add_co_u32_e64 v236, s[16:17], s26, v236
	v_lshl_add_u64 v[238:239], v[38:39], 0, v[238:239]
	s_nop 0
	v_addc_co_u32_e64 v237, s[16:17], 0, v237, s[16:17]
	global_load_dword v187, v[238:239], off sc0 sc1
	global_load_ushort v188, v[236:237], off offset:256 sc0 sc1
	v_add_u32_e32 v236, s2, v108
	v_ashrrev_i32_e32 v237, 31, v236
	v_lshlrev_b64 v[238:239], 10, v[236:237]
	v_lshlrev_b64 v[236:237], 9, v[236:237]
	v_lshl_add_u64 v[236:237], s[46:47], 0, v[236:237]
	v_lshl_add_u64 v[236:237], v[236:237], 0, v[176:177]
	v_add_co_u32_e64 v236, s[16:17], s26, v236
	v_lshl_add_u64 v[238:239], v[38:39], 0, v[238:239]
	s_nop 0
	v_addc_co_u32_e64 v237, s[16:17], 0, v237, s[16:17]
	global_load_dword v189, v[238:239], off sc0 sc1
	global_load_ushort v190, v[236:237], off offset:256 sc0 sc1
	v_add_u32_e32 v236, s2, v109
	v_ashrrev_i32_e32 v237, 31, v236
	v_lshlrev_b64 v[238:239], 10, v[236:237]
	v_lshlrev_b64 v[236:237], 9, v[236:237]
	v_lshl_add_u64 v[236:237], s[46:47], 0, v[236:237]
	v_lshl_add_u64 v[236:237], v[236:237], 0, v[176:177]
	v_add_co_u32_e64 v236, s[16:17], s26, v236
	v_lshl_add_u64 v[238:239], v[38:39], 0, v[238:239]
	s_nop 0
	v_addc_co_u32_e64 v237, s[16:17], 0, v237, s[16:17]
	global_load_dword v191, v[238:239], off sc0 sc1
	global_load_ushort v192, v[236:237], off offset:256 sc0 sc1
	v_add_u32_e32 v236, s2, v110
	v_ashrrev_i32_e32 v237, 31, v236
	v_lshlrev_b64 v[238:239], 10, v[236:237]
	v_lshlrev_b64 v[236:237], 9, v[236:237]
	v_lshl_add_u64 v[236:237], s[46:47], 0, v[236:237]
	v_lshl_add_u64 v[236:237], v[236:237], 0, v[176:177]
	v_add_co_u32_e64 v236, s[16:17], s26, v236
	v_lshl_add_u64 v[238:239], v[38:39], 0, v[238:239]
	s_nop 0
	v_addc_co_u32_e64 v237, s[16:17], 0, v237, s[16:17]
	global_load_dword v193, v[238:239], off sc0 sc1
	global_load_ushort v194, v[236:237], off offset:256 sc0 sc1
	v_add_u32_e32 v236, s2, v111
	v_ashrrev_i32_e32 v237, 31, v236
	v_lshlrev_b64 v[238:239], 10, v[236:237]
	v_lshlrev_b64 v[236:237], 9, v[236:237]
	v_lshl_add_u64 v[236:237], s[46:47], 0, v[236:237]
	v_lshl_add_u64 v[236:237], v[236:237], 0, v[176:177]
	v_add_co_u32_e64 v236, s[16:17], s26, v236
	v_lshl_add_u64 v[238:239], v[38:39], 0, v[238:239]
	s_nop 0
	v_addc_co_u32_e64 v237, s[16:17], 0, v237, s[16:17]
	global_load_dword v195, v[238:239], off sc0 sc1
	global_load_ushort v196, v[236:237], off offset:256 sc0 sc1
	v_add_u32_e32 v236, s2, v112
	v_ashrrev_i32_e32 v237, 31, v236
	v_lshlrev_b64 v[236:237], 9, v[236:237]
	v_lshl_add_u64 v[236:237], v[40:41], 0, v[236:237]
	global_load_ushort v197, v[236:237], off sc0 sc1
	v_add_u32_e32 v236, s2, v113
	v_ashrrev_i32_e32 v237, 31, v236
	v_lshlrev_b64 v[236:237], 9, v[236:237]
	v_lshl_add_u64 v[236:237], v[40:41], 0, v[236:237]
	global_load_ushort v198, v[236:237], off sc0 sc1
	v_add_u32_e32 v236, s2, v114
	v_ashrrev_i32_e32 v237, 31, v236
	v_lshlrev_b64 v[236:237], 9, v[236:237]
	v_lshl_add_u64 v[236:237], v[40:41], 0, v[236:237]
	global_load_ushort v199, v[236:237], off sc0 sc1
	v_add_u32_e32 v236, s2, v115
	v_ashrrev_i32_e32 v237, 31, v236
	v_lshlrev_b64 v[236:237], 9, v[236:237]
	v_lshl_add_u64 v[236:237], v[40:41], 0, v[236:237]
	global_load_ushort v200, v[236:237], off sc0 sc1
	v_add_u32_e32 v236, s2, v116
	v_ashrrev_i32_e32 v237, 31, v236
	v_lshlrev_b64 v[236:237], 9, v[236:237]
	v_lshl_add_u64 v[236:237], v[40:41], 0, v[236:237]
	global_load_ushort v201, v[236:237], off sc0 sc1
	v_add_u32_e32 v236, s2, v117
	v_ashrrev_i32_e32 v237, 31, v236
	v_lshlrev_b64 v[236:237], 9, v[236:237]
	v_lshl_add_u64 v[236:237], v[40:41], 0, v[236:237]
	global_load_ushort v213, v[236:237], off sc0 sc1
	v_add_u32_e32 v236, s2, v118
	v_ashrrev_i32_e32 v237, 31, v236
	v_lshlrev_b64 v[236:237], 9, v[236:237]
	v_lshl_add_u64 v[236:237], v[40:41], 0, v[236:237]
	global_load_ushort v214, v[236:237], off sc0 sc1
	v_add_u32_e32 v236, s2, v119
	v_ashrrev_i32_e32 v237, 31, v236
	v_lshlrev_b64 v[236:237], 9, v[236:237]
	v_lshl_add_u64 v[236:237], v[40:41], 0, v[236:237]
	global_load_ushort v215, v[236:237], off sc0 sc1
	s_branch .LBB0_311

.LBB0_311:
	s_waitcnt vmcnt(0)
	v_mov_b32_e32 v120, v159
	v_mov_b32_e32 v121, v160
	v_mov_b32_e32 v124, v161
	v_mov_b32_e32 v122, v162
	v_mov_b32_e32 v125, v163
	v_mov_b32_e32 v123, v164
	v_mov_b32_e32 v127, v165
	v_mov_b32_e32 v126, v166
	v_mov_b32_e32 v129, v167
	v_mov_b32_e32 v128, v168
	v_mov_b32_e32 v130, v169
	v_mov_b32_e32 v131, v170
	v_mov_b32_e32 v134, v171
	v_mov_b32_e32 v132, v172
	v_mov_b32_e32 v135, v173
	v_mov_b32_e32 v133, v174
	v_mov_b32_e32 v138, v175
	v_mov_b32_e32 v136, v182
	v_mov_b32_e32 v139, v183
	v_mov_b32_e32 v137, v184
	v_mov_b32_e32 v153, v185
	v_mov_b32_e32 v140, v186
	v_mov_b32_e32 v154, v187
	v_mov_b32_e32 v141, v188
	v_mov_b32_e32 v155, v189
	v_mov_b32_e32 v142, v190
	v_mov_b32_e32 v156, v191
	v_mov_b32_e32 v145, v192
	v_mov_b32_e32 v157, v193
	v_mov_b32_e32 v146, v194
	v_mov_b32_e32 v158, v195
	v_mov_b32_e32 v149, v196
	v_mov_b32_e32 v18, v197
	v_mov_b32_e32 v19, v198
	v_mov_b32_e32 v143, v199
	v_mov_b32_e32 v144, v200
	v_mov_b32_e32 v147, v201
	v_mov_b32_e32 v148, v213
	v_mov_b32_e32 v150, v214
	v_mov_b32_e32 v16, v215
	s_cmp_eq_u32 s25, 0
	s_cbranch_scc1 .Lsa_nopf
	s_add_i32 s16, s23, 64
	s_sub_i32 s17, s25, 64
	s_and_b64 s[2:3], s[14:15], exec
	s_cselect_b32 s2, s16, s17
	s_add_i32 s2, s2, s24
	v_add_u32_e32 v236, s2, v37
	v_ashrrev_i32_e32 v237, 31, v236
	v_lshlrev_b64 v[238:239], 10, v[236:237]
	v_lshlrev_b64 v[236:237], 9, v[236:237]
	v_lshl_add_u64 v[236:237], s[46:47], 0, v[236:237]
	v_lshl_add_u64 v[236:237], v[236:237], 0, v[176:177]
	v_add_co_u32_e64 v236, s[16:17], s26, v236
	v_lshl_add_u64 v[238:239], v[38:39], 0, v[238:239]
	s_nop 0
	v_addc_co_u32_e64 v237, s[16:17], 0, v237, s[16:17]
	global_load_dword v159, v[238:239], off sc0 sc1
	global_load_ushort v160, v[236:237], off offset:256 sc0 sc1
	v_add_u32_e32 v236, s2, v97
	v_ashrrev_i32_e32 v237, 31, v236
	v_lshlrev_b64 v[238:239], 10, v[236:237]
	v_lshlrev_b64 v[236:237], 9, v[236:237]
	v_lshl_add_u64 v[236:237], s[46:47], 0, v[236:237]
	v_lshl_add_u64 v[236:237], v[236:237], 0, v[176:177]
	v_add_co_u32_e64 v236, s[16:17], s26, v236
	v_lshl_add_u64 v[238:239], v[38:39], 0, v[238:239]
	s_nop 0
	v_addc_co_u32_e64 v237, s[16:17], 0, v237, s[16:17]
	global_load_dword v161, v[238:239], off sc0 sc1
	global_load_ushort v162, v[236:237], off offset:256 sc0 sc1
	v_add_u32_e32 v236, s2, v98
	v_ashrrev_i32_e32 v237, 31, v236
	v_lshlrev_b64 v[238:239], 10, v[236:237]
	v_lshlrev_b64 v[236:237], 9, v[236:237]
	v_lshl_add_u64 v[236:237], s[46:47], 0, v[236:237]
	v_lshl_add_u64 v[236:237], v[236:237], 0, v[176:177]
	v_add_co_u32_e64 v236, s[16:17], s26, v236
	v_lshl_add_u64 v[238:239], v[38:39], 0, v[238:239]
	s_nop 0
	v_addc_co_u32_e64 v237, s[16:17], 0, v237, s[16:17]
	global_load_dword v163, v[238:239], off sc0 sc1
	global_load_ushort v164, v[236:237], off offset:256 sc0 sc1
	v_add_u32_e32 v236, s2, v99
	v_ashrrev_i32_e32 v237, 31, v236
	v_lshlrev_b64 v[238:239], 10, v[236:237]
	v_lshlrev_b64 v[236:237], 9, v[236:237]
	v_lshl_add_u64 v[236:237], s[46:47], 0, v[236:237]
	v_lshl_add_u64 v[236:237], v[236:237], 0, v[176:177]
	v_add_co_u32_e64 v236, s[16:17], s26, v236
	v_lshl_add_u64 v[238:239], v[38:39], 0, v[238:239]
	s_nop 0
	v_addc_co_u32_e64 v237, s[16:17], 0, v237, s[16:17]
	global_load_dword v165, v[238:239], off sc0 sc1
	global_load_ushort v166, v[236:237], off offset:256 sc0 sc1
	v_add_u32_e32 v236, s2, v100
	v_ashrrev_i32_e32 v237, 31, v236
	v_lshlrev_b64 v[238:239], 10, v[236:237]
	v_lshlrev_b64 v[236:237], 9, v[236:237]
	v_lshl_add_u64 v[236:237], s[46:47], 0, v[236:237]
	v_lshl_add_u64 v[236:237], v[236:237], 0, v[176:177]
	v_add_co_u32_e64 v236, s[16:17], s26, v236
	v_lshl_add_u64 v[238:239], v[38:39], 0, v[238:239]
	s_nop 0
	v_addc_co_u32_e64 v237, s[16:17], 0, v237, s[16:17]
	global_load_dword v167, v[238:239], off sc0 sc1
	global_load_ushort v168, v[236:237], off offset:256 sc0 sc1
	v_add_u32_e32 v236, s2, v101
	v_ashrrev_i32_e32 v237, 31, v236
	v_lshlrev_b64 v[238:239], 10, v[236:237]
	v_lshlrev_b64 v[236:237], 9, v[236:237]
	v_lshl_add_u64 v[236:237], s[46:47], 0, v[236:237]
	v_lshl_add_u64 v[236:237], v[236:237], 0, v[176:177]
	v_add_co_u32_e64 v236, s[16:17], s26, v236
	v_lshl_add_u64 v[238:239], v[38:39], 0, v[238:239]
	s_nop 0
	v_addc_co_u32_e64 v237, s[16:17], 0, v237, s[16:17]
	global_load_dword v169, v[238:239], off sc0 sc1
	global_load_ushort v170, v[236:237], off offset:256 sc0 sc1
	v_add_u32_e32 v236, s2, v102
	v_ashrrev_i32_e32 v237, 31, v236
	v_lshlrev_b64 v[238:239], 10, v[236:237]
	v_lshlrev_b64 v[236:237], 9, v[236:237]
	v_lshl_add_u64 v[236:237], s[46:47], 0, v[236:237]
	v_lshl_add_u64 v[236:237], v[236:237], 0, v[176:177]
	v_add_co_u32_e64 v236, s[16:17], s26, v236
	v_lshl_add_u64 v[238:239], v[38:39], 0, v[238:239]
	s_nop 0
	v_addc_co_u32_e64 v237, s[16:17], 0, v237, s[16:17]
	global_load_dword v171, v[238:239], off sc0 sc1
	global_load_ushort v172, v[236:237], off offset:256 sc0 sc1
	v_add_u32_e32 v236, s2, v103
	v_ashrrev_i32_e32 v237, 31, v236
	v_lshlrev_b64 v[238:239], 10, v[236:237]
	v_lshlrev_b64 v[236:237], 9, v[236:237]
	v_lshl_add_u64 v[236:237], s[46:47], 0, v[236:237]
	v_lshl_add_u64 v[236:237], v[236:237], 0, v[176:177]
	v_add_co_u32_e64 v236, s[16:17], s26, v236
	v_lshl_add_u64 v[238:239], v[38:39], 0, v[238:239]
	s_nop 0
	v_addc_co_u32_e64 v237, s[16:17], 0, v237, s[16:17]
	global_load_dword v173, v[238:239], off sc0 sc1
	global_load_ushort v174, v[236:237], off offset:256 sc0 sc1
	v_add_u32_e32 v236, s2, v104
	v_ashrrev_i32_e32 v237, 31, v236
	v_lshlrev_b64 v[238:239], 10, v[236:237]
	v_lshlrev_b64 v[236:237], 9, v[236:237]
	v_lshl_add_u64 v[236:237], s[46:47], 0, v[236:237]
	v_lshl_add_u64 v[236:237], v[236:237], 0, v[176:177]
	v_add_co_u32_e64 v236, s[16:17], s26, v236
	v_lshl_add_u64 v[238:239], v[38:39], 0, v[238:239]
	s_nop 0
	v_addc_co_u32_e64 v237, s[16:17], 0, v237, s[16:17]
	global_load_dword v175, v[238:239], off sc0 sc1
	global_load_ushort v182, v[236:237], off offset:256 sc0 sc1
	v_add_u32_e32 v236, s2, v105
	v_ashrrev_i32_e32 v237, 31, v236
	v_lshlrev_b64 v[238:239], 10, v[236:237]
	v_lshlrev_b64 v[236:237], 9, v[236:237]
	v_lshl_add_u64 v[236:237], s[46:47], 0, v[236:237]
	v_lshl_add_u64 v[236:237], v[236:237], 0, v[176:177]
	v_add_co_u32_e64 v236, s[16:17], s26, v236
	v_lshl_add_u64 v[238:239], v[38:39], 0, v[238:239]
	s_nop 0
	v_addc_co_u32_e64 v237, s[16:17], 0, v237, s[16:17]
	global_load_dword v183, v[238:239], off sc0 sc1
	global_load_ushort v184, v[236:237], off offset:256 sc0 sc1
	v_add_u32_e32 v236, s2, v106
	v_ashrrev_i32_e32 v237, 31, v236
	v_lshlrev_b64 v[238:239], 10, v[236:237]
	v_lshlrev_b64 v[236:237], 9, v[236:237]
	v_lshl_add_u64 v[236:237], s[46:47], 0, v[236:237]
	v_lshl_add_u64 v[236:237], v[236:237], 0, v[176:177]
	v_add_co_u32_e64 v236, s[16:17], s26, v236
	v_lshl_add_u64 v[238:239], v[38:39], 0, v[238:239]
	s_nop 0
	v_addc_co_u32_e64 v237, s[16:17], 0, v237, s[16:17]
	global_load_dword v185, v[238:239], off sc0 sc1
	global_load_ushort v186, v[236:237], off offset:256 sc0 sc1
	v_add_u32_e32 v236, s2, v107
	v_ashrrev_i32_e32 v237, 31, v236
	v_lshlrev_b64 v[238:239], 10, v[236:237]
	v_lshlrev_b64 v[236:237], 9, v[236:237]
	v_lshl_add_u64 v[236:237], s[46:47], 0, v[236:237]
	v_lshl_add_u64 v[236:237], v[236:237], 0, v[176:177]
	v_add_co_u32_e64 v236, s[16:17], s26, v236
	v_lshl_add_u64 v[238:239], v[38:39], 0, v[238:239]
	s_nop 0
	v_addc_co_u32_e64 v237, s[16:17], 0, v237, s[16:17]
	global_load_dword v187, v[238:239], off sc0 sc1
	global_load_ushort v188, v[236:237], off offset:256 sc0 sc1
	v_add_u32_e32 v236, s2, v108
	v_ashrrev_i32_e32 v237, 31, v236
	v_lshlrev_b64 v[238:239], 10, v[236:237]
	v_lshlrev_b64 v[236:237], 9, v[236:237]
	v_lshl_add_u64 v[236:237], s[46:47], 0, v[236:237]
	v_lshl_add_u64 v[236:237], v[236:237], 0, v[176:177]
	v_add_co_u32_e64 v236, s[16:17], s26, v236
	v_lshl_add_u64 v[238:239], v[38:39], 0, v[238:239]
	s_nop 0
	v_addc_co_u32_e64 v237, s[16:17], 0, v237, s[16:17]
	global_load_dword v189, v[238:239], off sc0 sc1
	global_load_ushort v190, v[236:237], off offset:256 sc0 sc1
	v_add_u32_e32 v236, s2, v109
	v_ashrrev_i32_e32 v237, 31, v236
	v_lshlrev_b64 v[238:239], 10, v[236:237]
	v_lshlrev_b64 v[236:237], 9, v[236:237]
	v_lshl_add_u64 v[236:237], s[46:47], 0, v[236:237]
	v_lshl_add_u64 v[236:237], v[236:237], 0, v[176:177]
	v_add_co_u32_e64 v236, s[16:17], s26, v236
	v_lshl_add_u64 v[238:239], v[38:39], 0, v[238:239]
	s_nop 0
	v_addc_co_u32_e64 v237, s[16:17], 0, v237, s[16:17]
	global_load_dword v191, v[238:239], off sc0 sc1
	global_load_ushort v192, v[236:237], off offset:256 sc0 sc1
	v_add_u32_e32 v236, s2, v110
	v_ashrrev_i32_e32 v237, 31, v236
	v_lshlrev_b64 v[238:239], 10, v[236:237]
	v_lshlrev_b64 v[236:237], 9, v[236:237]
	v_lshl_add_u64 v[236:237], s[46:47], 0, v[236:237]
	v_lshl_add_u64 v[236:237], v[236:237], 0, v[176:177]
	v_add_co_u32_e64 v236, s[16:17], s26, v236
	v_lshl_add_u64 v[238:239], v[38:39], 0, v[238:239]
	s_nop 0
	v_addc_co_u32_e64 v237, s[16:17], 0, v237, s[16:17]
	global_load_dword v193, v[238:239], off sc0 sc1
	global_load_ushort v194, v[236:237], off offset:256 sc0 sc1
	v_add_u32_e32 v236, s2, v111
	v_ashrrev_i32_e32 v237, 31, v236
	v_lshlrev_b64 v[238:239], 10, v[236:237]
	v_lshlrev_b64 v[236:237], 9, v[236:237]
	v_lshl_add_u64 v[236:237], s[46:47], 0, v[236:237]
	v_lshl_add_u64 v[236:237], v[236:237], 0, v[176:177]
	v_add_co_u32_e64 v236, s[16:17], s26, v236
	v_lshl_add_u64 v[238:239], v[38:39], 0, v[238:239]
	s_nop 0
	v_addc_co_u32_e64 v237, s[16:17], 0, v237, s[16:17]
	global_load_dword v195, v[238:239], off sc0 sc1
	global_load_ushort v196, v[236:237], off offset:256 sc0 sc1
	v_add_u32_e32 v236, s2, v112
	v_ashrrev_i32_e32 v237, 31, v236
	v_lshlrev_b64 v[236:237], 9, v[236:237]
	v_lshl_add_u64 v[236:237], v[40:41], 0, v[236:237]
	global_load_ushort v197, v[236:237], off sc0 sc1
	v_add_u32_e32 v236, s2, v113
	v_ashrrev_i32_e32 v237, 31, v236
	v_lshlrev_b64 v[236:237], 9, v[236:237]
	v_lshl_add_u64 v[236:237], v[40:41], 0, v[236:237]
	global_load_ushort v198, v[236:237], off sc0 sc1
	v_add_u32_e32 v236, s2, v114
	v_ashrrev_i32_e32 v237, 31, v236
	v_lshlrev_b64 v[236:237], 9, v[236:237]
	v_lshl_add_u64 v[236:237], v[40:41], 0, v[236:237]
	global_load_ushort v199, v[236:237], off sc0 sc1
	v_add_u32_e32 v236, s2, v115
	v_ashrrev_i32_e32 v237, 31, v236
	v_lshlrev_b64 v[236:237], 9, v[236:237]
	v_lshl_add_u64 v[236:237], v[40:41], 0, v[236:237]
	global_load_ushort v200, v[236:237], off sc0 sc1
	v_add_u32_e32 v236, s2, v116
	v_ashrrev_i32_e32 v237, 31, v236
	v_lshlrev_b64 v[236:237], 9, v[236:237]
	v_lshl_add_u64 v[236:237], v[40:41], 0, v[236:237]
	global_load_ushort v201, v[236:237], off sc0 sc1
	v_add_u32_e32 v236, s2, v117
	v_ashrrev_i32_e32 v237, 31, v236
	v_lshlrev_b64 v[236:237], 9, v[236:237]
	v_lshl_add_u64 v[236:237], v[40:41], 0, v[236:237]
	global_load_ushort v213, v[236:237], off sc0 sc1
	v_add_u32_e32 v236, s2, v118
	v_ashrrev_i32_e32 v237, 31, v236
	v_lshlrev_b64 v[236:237], 9, v[236:237]
	v_lshl_add_u64 v[236:237], v[40:41], 0, v[236:237]
	global_load_ushort v214, v[236:237], off sc0 sc1
	v_add_u32_e32 v236, s2, v119
	v_ashrrev_i32_e32 v237, 31, v236
	v_lshlrev_b64 v[236:237], 9, v[236:237]
	v_lshl_add_u64 v[236:237], v[40:41], 0, v[236:237]
	global_load_ushort v215, v[236:237], off sc0 sc1
.Lsa_nopf:
	v_add_f32_e32 v152, v120, v124
	v_lshlrev_b32_e32 v17, 16, v18
	v_lshlrev_b32_e32 v18, 16, v19
	v_lshlrev_b32_e32 v19, 16, v143
	v_lshlrev_b32_e32 v143, 16, v144
	v_lshlrev_b32_e32 v144, 16, v147
	v_lshlrev_b32_e32 v147, 16, v148
	v_lshlrev_b32_e32 v148, 16, v150
	v_lshlrev_b32_e32 v150, 16, v16
	v_cvt_pk_bf16_f32 v16, v17, v18
	v_cvt_pk_bf16_f32 v17, v19, v143
	v_cvt_pk_bf16_f32 v18, v144, v147
	v_cvt_pk_bf16_f32 v19, v148, v150
	v_add_f32_e32 v150, v152, v125
	v_add_f32_e32 v151, v150, v127
	v_add_f32_e32 v147, v151, v129
	v_add_f32_e32 v148, v147, v130
	v_add_f32_e32 v143, v148, v134
	v_add_f32_e32 v144, v143, v135
	v_add_f32_e32 v138, v144, v138
	v_add_f32_e32 v139, v138, v139
	v_add_f32_e32 v134, v139, v153
	v_add_f32_e32 v135, v134, v154
	v_add_f32_e32 v129, v135, v155
	v_add_f32_e32 v130, v129, v156
	v_add_f32_e32 v124, v130, v157
	v_add_f32_e32 v125, v124, v158
	ds_write_b32 v44, v125
	ds_write_b128 v92, v[16:19] offset:53248
	s_waitcnt lgkmcnt(0)
	s_barrier
	ds_read2st64_b32 v[18:19], v45 offset1:2
	ds_read2st64_b32 v[16:17], v45 offset0:4 offset1:6
	s_waitcnt lgkmcnt(1)
	v_add_f32_e32 v18, 0, v18
	v_add_f32_e32 v127, v18, v19
	s_waitcnt lgkmcnt(0)
	v_add_f32_e32 v127, v127, v16
	v_add_f32_e32 v127, v127, v17
	s_and_saveexec_b64 s[2:3], vcc
	s_cbranch_execz .LBB0_310
	v_mul_f32_e32 v153, 0x3fb8aa3b, v127
	v_exp_f32_e32 v153, v153
	v_add_f32_e32 v96, v96, v127
	ds_write_b32 v46, v153
	s_branch .LBB0_310
